# retention item epilogue: the 15 later gate/gn load pairs issued up front into dead Q/loop registers, exact counted vmcnt per step instead of 16 serialized round trips
# speedup vs baseline: 1.0127x; 1.0035x over previous
.LBB0_752:
	s_or_b64 exec, exec, s[26:27]
	s_and_b32 s0, s55, 0x60
	v_add_u32_e32 v66, s7, v189
	s_lshl_b32 s0, s0, 2
	v_ashrrev_i32_e32 v67, 31, v66
	s_add_i32 s0, s0, 0
	v_lshlrev_b64 v[68:69], 12, v[66:67]
	s_ashr_i32 s7, s6, 31
	v_mov_b64_e32 v[70:71], s[20:21]
	s_movk_i32 s4, 0x3000
	v_lshl_add_u32 v64, v189, 2, s0
	v_lshl_add_u64 v[68:69], s[20:21], 0, v[68:69]
	s_lshl_b64 s[0:1], s[6:7], 1
	v_mad_i64_i32 v[66:67], s[4:5], v66, s4, v[70:71]
	s_waitcnt lgkmcnt(0)
	s_barrier
	v_lshl_add_u64 v[68:69], v[68:69], 0, s[0:1]
	v_lshl_add_u64 v[66:67], v[66:67], 0, s[0:1]
	s_load_dwordx2 s[0:1], s[66:67], 0xc0
	s_lshl_b64 s[4:5], s[6:7], 2
	v_lshlrev_b32_e32 v74, 1, v190
	v_mov_b32_e32 v75, v112
	v_lshl_add_u64 v[70:71], v[66:67], 0, v[74:75]
	s_waitcnt lgkmcnt(0)
	s_add_u32 s6, s0, s4
	s_addc_u32 s7, s1, s5
	s_mov_b64 s[0:1], 0x4802000
	v_lshl_add_u64 v[66:67], v[70:71], 0, s[0:1]
	s_mov_b32 s0, 0x4802000
	v_add_co_u32_e32 v70, vcc, s0, v70
	v_lshlrev_b32_e32 v65, 2, v190
	s_nop 0
	v_addc_co_u32_e32 v71, vcc, 0, v71, vcc
	global_load_dwordx2 v[76:77], v[70:71], off
	ds_read_b32 v64, v64 offset:1024
	global_load_dwordx4 v[70:73], v65, s[6:7]
	global_load_dwordx2 v[142:143], v[66:67], off offset:16
	global_load_dwordx4 v[214:217], v65, s[6:7] offset:32
	global_load_dwordx2 v[144:145], v[66:67], off offset:32
	global_load_dwordx4 v[218:221], v65, s[6:7] offset:64
	global_load_dwordx2 v[146:147], v[66:67], off offset:48
	global_load_dwordx4 v[222:225], v65, s[6:7] offset:96
	global_load_dwordx2 v[148:149], v[66:67], off offset:64
	global_load_dwordx4 v[226:229], v65, s[6:7] offset:128
	global_load_dwordx2 v[150:151], v[66:67], off offset:80
	global_load_dwordx4 v[230:233], v65, s[6:7] offset:160
	global_load_dwordx2 v[152:153], v[66:67], off offset:96
	global_load_dwordx4 v[234:237], v65, s[6:7] offset:192
	global_load_dwordx2 v[154:155], v[66:67], off offset:112
	global_load_dwordx4 v[238:241], v65, s[6:7] offset:224
	global_load_dwordx2 v[156:157], v[66:67], off offset:128
	global_load_dwordx4 v[242:245], v65, s[6:7] offset:256
	global_load_dwordx2 v[158:159], v[66:67], off offset:144
	global_load_dwordx4 v[246:249], v65, s[6:7] offset:288
	global_load_dwordx2 v[160:161], v[66:67], off offset:160
	global_load_dwordx4 v[182:185], v65, s[6:7] offset:320
	global_load_dwordx2 v[170:171], v[66:67], off offset:176
	global_load_dwordx4 v[84:87], v65, s[6:7] offset:352
	global_load_dwordx2 v[172:173], v[66:67], off offset:192
	global_load_dwordx4 v[92:95], v65, s[6:7] offset:384
	global_load_dwordx2 v[174:175], v[66:67], off offset:208
	global_load_dwordx4 v[102:105], v65, s[6:7] offset:416
	global_load_dwordx2 v[176:177], v[66:67], off offset:224
	global_load_dwordx4 v[122:125], v65, s[6:7] offset:448
	global_load_dwordx2 v[178:179], v[66:67], off offset:240
	global_load_dwordx4 v[130:133], v65, s[6:7] offset:480
	s_mov_b64 s[0:1], 0x12c00000
	s_waitcnt lgkmcnt(0)
	v_pk_mul_f32 v[48:49], v[48:49], v[64:65] op_sel_hi:[1,0]
	v_pk_mul_f32 v[50:51], v[50:51], v[64:65] op_sel_hi:[1,0]
	v_pk_mul_f32 v[52:53], v[52:53], v[64:65] op_sel_hi:[1,0]
	v_pk_mul_f32 v[54:55], v[54:55], v[64:65] op_sel_hi:[1,0]
	v_pk_mul_f32 v[56:57], v[56:57], v[64:65] op_sel_hi:[1,0]
	v_pk_mul_f32 v[32:33], v[32:33], v[64:65] op_sel_hi:[1,0]
	v_pk_mul_f32 v[34:35], v[34:35], v[64:65] op_sel_hi:[1,0]
	v_pk_mul_f32 v[36:37], v[36:37], v[64:65] op_sel_hi:[1,0]
	v_pk_mul_f32 v[38:39], v[38:39], v[64:65] op_sel_hi:[1,0]
	v_pk_mul_f32 v[40:41], v[40:41], v[64:65] op_sel_hi:[1,0]
	v_pk_mul_f32 v[16:17], v[16:17], v[64:65] op_sel_hi:[1,0]
	v_pk_mul_f32 v[18:19], v[18:19], v[64:65] op_sel_hi:[1,0]
	v_pk_mul_f32 v[20:21], v[20:21], v[64:65] op_sel_hi:[1,0]
	v_pk_mul_f32 v[22:23], v[22:23], v[64:65] op_sel_hi:[1,0]
	v_pk_mul_f32 v[24:25], v[24:25], v[64:65] op_sel_hi:[1,0]
	v_pk_mul_f32 v[0:1], v[0:1], v[64:65] op_sel_hi:[1,0]
	v_pk_mul_f32 v[2:3], v[2:3], v[64:65] op_sel_hi:[1,0]
	v_pk_mul_f32 v[4:5], v[4:5], v[64:65] op_sel_hi:[1,0]
	v_pk_mul_f32 v[6:7], v[6:7], v[64:65] op_sel_hi:[1,0]
	v_pk_mul_f32 v[8:9], v[8:9], v[64:65] op_sel_hi:[1,0]
	s_waitcnt vmcnt(31)
	v_lshlrev_b32_e32 v78, 16, v76
	v_and_b32_e32 v79, 0xffff0000, v76
	v_mul_f32_e32 v76, 0xbfb8aa3b, v78
	v_exp_f32_e32 v76, v76
	s_waitcnt vmcnt(30)
	v_pk_mul_f32 v[48:49], v[48:49], v[70:71]
	v_lshlrev_b32_e32 v70, 16, v77
	v_and_b32_e32 v71, 0xffff0000, v77
	v_add_f32_e32 v76, 1.0, v76
	v_rcp_f32_e32 v80, v76
	v_mul_f32_e32 v76, 0xbfb8aa3b, v79
	v_exp_f32_e32 v76, v76
	v_mul_f32_e32 v77, 0xbfb8aa3b, v71
	v_exp_f32_e32 v77, v77
	v_pk_mul_f32 v[50:51], v[50:51], v[72:73]
	v_add_f32_e32 v76, 1.0, v76
	v_rcp_f32_e32 v81, v76
	v_mul_f32_e32 v76, 0xbfb8aa3b, v70
	v_exp_f32_e32 v76, v76
	v_add_f32_e32 v77, 1.0, v77
	v_rcp_f32_e32 v77, v77
	v_pk_mul_f32 v[78:79], v[80:81], v[78:79]
	v_add_f32_e32 v76, 1.0, v76
	v_rcp_f32_e32 v76, v76
	v_pk_mul_f32 v[48:49], v[48:49], v[78:79]
	v_pk_mul_f32 v[70:71], v[76:77], v[70:71]
	s_nop 0
	v_pk_mul_f32 v[50:51], v[50:51], v[70:71]
	v_cvt_pk_bf16_f32 v70, v48, v49
	v_cvt_pk_bf16_f32 v71, v50, v51
	v_lshl_add_u64 v[50:51], v[68:69], 0, v[74:75]
	v_lshl_add_u64 v[48:49], v[50:51], 0, s[0:1]
	s_mov_b32 s0, 0x12c00000
	v_add_co_u32_e32 v50, vcc, s0, v50
	s_nop 1
	v_addc_co_u32_e32 v51, vcc, 0, v51, vcc
	global_store_dwordx2 v[50:51], v[70:71], off
	s_nop 0
	s_waitcnt vmcnt(30)
	v_lshlrev_b32_e32 v72, 16, v142
	v_and_b32_e32 v73, 0xffff0000, v142
	v_mul_f32_e32 v50, 0xbfb8aa3b, v72
	v_exp_f32_e32 v50, v50
	s_waitcnt vmcnt(29)
	v_pk_mul_f32 v[52:53], v[52:53], v[214:215]
	v_pk_mul_f32 v[54:55], v[54:55], v[216:217]
	v_add_f32_e32 v50, 1.0, v50
	v_rcp_f32_e32 v74, v50
	v_mul_f32_e32 v50, 0xbfb8aa3b, v73
	v_exp_f32_e32 v50, v50
	s_nop 0
	v_add_f32_e32 v50, 1.0, v50
	v_rcp_f32_e32 v75, v50
	v_lshlrev_b32_e32 v50, 16, v143
	v_and_b32_e32 v51, 0xffff0000, v143
	v_mul_f32_e32 v68, 0xbfb8aa3b, v50
	v_mul_f32_e32 v69, 0xbfb8aa3b, v51
	v_exp_f32_e32 v68, v68
	v_exp_f32_e32 v69, v69
	v_pk_mul_f32 v[72:73], v[74:75], v[72:73]
	v_add_f32_e32 v68, 1.0, v68
	v_add_f32_e32 v69, 1.0, v69
	v_rcp_f32_e32 v68, v68
	v_rcp_f32_e32 v69, v69
	v_pk_mul_f32 v[52:53], v[52:53], v[72:73]
	v_pk_mul_f32 v[50:51], v[68:69], v[50:51]
	s_nop 0
	v_pk_mul_f32 v[50:51], v[54:55], v[50:51]
	v_cvt_pk_bf16_f32 v52, v52, v53
	v_cvt_pk_bf16_f32 v53, v50, v51
	global_store_dwordx2 v[48:49], v[52:53], off offset:16
	s_nop 0
	s_waitcnt vmcnt(29)
	v_lshlrev_b32_e32 v68, 16, v144
	v_and_b32_e32 v69, 0xffff0000, v144
	v_mul_f32_e32 v54, 0xbfb8aa3b, v68
	v_exp_f32_e32 v54, v54
	s_waitcnt vmcnt(28)
	v_pk_mul_f32 v[50:51], v[56:57], v[218:219]
	v_add_f32_e32 v54, 1.0, v54
	v_rcp_f32_e32 v70, v54
	v_mul_f32_e32 v54, 0xbfb8aa3b, v69
	v_exp_f32_e32 v54, v54
	s_nop 0
	v_add_f32_e32 v54, 1.0, v54
	v_rcp_f32_e32 v71, v54
	v_lshlrev_b32_e32 v54, 16, v145
	v_and_b32_e32 v55, 0xffff0000, v145
	v_mul_f32_e32 v56, 0xbfb8aa3b, v54
	v_mul_f32_e32 v57, 0xbfb8aa3b, v55
	v_exp_f32_e32 v56, v56
	v_exp_f32_e32 v57, v57
	v_pk_mul_f32 v[68:69], v[70:71], v[68:69]
	v_add_f32_e32 v56, 1.0, v56
	v_add_f32_e32 v57, 1.0, v57
	v_rcp_f32_e32 v56, v56
	v_rcp_f32_e32 v57, v57
	v_pk_mul_f32 v[50:51], v[50:51], v[68:69]
	v_pk_mul_f32 v[54:55], v[56:57], v[54:55]
	v_pk_mul_f32 v[56:57], v[58:59], v[64:65] op_sel_hi:[1,0]
	v_cvt_pk_bf16_f32 v50, v50, v51
	v_pk_mul_f32 v[52:53], v[56:57], v[220:221]
	s_nop 0
	v_pk_mul_f32 v[52:53], v[52:53], v[54:55]
	s_nop 0
	v_cvt_pk_bf16_f32 v51, v52, v53
	global_store_dwordx2 v[48:49], v[50:51], off offset:32
	s_nop 0
	s_waitcnt vmcnt(28)
	v_lshlrev_b32_e32 v56, 16, v146
	v_and_b32_e32 v57, 0xffff0000, v146
	v_mul_f32_e32 v54, 0xbfb8aa3b, v56
	v_exp_f32_e32 v54, v54
	s_nop 0
	v_add_f32_e32 v54, 1.0, v54
	v_rcp_f32_e32 v58, v54
	v_mul_f32_e32 v54, 0xbfb8aa3b, v57
	v_exp_f32_e32 v54, v54
	s_nop 0
	v_add_f32_e32 v54, 1.0, v54
	v_rcp_f32_e32 v59, v54
	v_lshlrev_b32_e32 v54, 16, v147
	v_and_b32_e32 v55, 0xffff0000, v147
	v_pk_mul_f32 v[56:57], v[58:59], v[56:57]
	v_pk_mul_f32 v[58:59], v[60:61], v[64:65] op_sel_hi:[1,0]
	s_waitcnt vmcnt(27)
	v_pk_mul_f32 v[50:51], v[58:59], v[222:223]
	s_nop 0
	v_pk_mul_f32 v[50:51], v[50:51], v[56:57]
	v_mul_f32_e32 v56, 0xbfb8aa3b, v54
	v_mul_f32_e32 v57, 0xbfb8aa3b, v55
	v_exp_f32_e32 v56, v56
	v_exp_f32_e32 v57, v57
	v_cvt_pk_bf16_f32 v50, v50, v51
	v_add_f32_e32 v56, 1.0, v56
	v_add_f32_e32 v57, 1.0, v57
	v_rcp_f32_e32 v56, v56
	v_rcp_f32_e32 v57, v57
	s_nop 0
	v_pk_mul_f32 v[54:55], v[56:57], v[54:55]
	v_pk_mul_f32 v[56:57], v[62:63], v[64:65] op_sel_hi:[1,0]
	s_nop 0
	v_pk_mul_f32 v[52:53], v[56:57], v[224:225]
	s_nop 0
	v_pk_mul_f32 v[52:53], v[52:53], v[54:55]
	s_nop 0
	v_cvt_pk_bf16_f32 v51, v52, v53
	global_store_dwordx2 v[48:49], v[50:51], off offset:48
	s_nop 0
	s_waitcnt vmcnt(27)
	v_lshlrev_b32_e32 v56, 16, v148
	v_and_b32_e32 v57, 0xffff0000, v148
	v_mul_f32_e32 v54, 0xbfb8aa3b, v56
	v_exp_f32_e32 v54, v54
	s_waitcnt vmcnt(26)
	v_pk_mul_f32 v[32:33], v[32:33], v[226:227]
	v_lshlrev_b32_e32 v50, 16, v149
	v_and_b32_e32 v51, 0xffff0000, v149
	v_add_f32_e32 v54, 1.0, v54
	v_rcp_f32_e32 v58, v54
	v_mul_f32_e32 v54, 0xbfb8aa3b, v57
	v_exp_f32_e32 v54, v54
	v_mul_f32_e32 v55, 0xbfb8aa3b, v51
	v_exp_f32_e32 v55, v55
	v_pk_mul_f32 v[34:35], v[34:35], v[228:229]
	v_add_f32_e32 v54, 1.0, v54
	v_rcp_f32_e32 v59, v54
	v_mul_f32_e32 v54, 0xbfb8aa3b, v50
	v_exp_f32_e32 v54, v54
	v_add_f32_e32 v55, 1.0, v55
	v_rcp_f32_e32 v55, v55
	v_pk_mul_f32 v[56:57], v[58:59], v[56:57]
	v_add_f32_e32 v54, 1.0, v54
	v_rcp_f32_e32 v54, v54
	v_pk_mul_f32 v[32:33], v[32:33], v[56:57]
	v_pk_mul_f32 v[50:51], v[54:55], v[50:51]
	s_nop 0
	v_pk_mul_f32 v[34:35], v[34:35], v[50:51]
	v_cvt_pk_bf16_f32 v32, v32, v33
	v_cvt_pk_bf16_f32 v33, v34, v35
	global_store_dwordx2 v[48:49], v[32:33], off offset:64
	s_nop 0
	s_waitcnt vmcnt(26)
	v_lshlrev_b32_e32 v52, 16, v150
	v_and_b32_e32 v53, 0xffff0000, v150
	v_mul_f32_e32 v50, 0xbfb8aa3b, v52
	v_exp_f32_e32 v50, v50
	s_waitcnt vmcnt(25)
	v_pk_mul_f32 v[32:33], v[36:37], v[230:231]
	v_lshlrev_b32_e32 v36, 16, v151
	v_and_b32_e32 v37, 0xffff0000, v151
	v_add_f32_e32 v50, 1.0, v50
	v_rcp_f32_e32 v54, v50
	v_mul_f32_e32 v50, 0xbfb8aa3b, v53
	v_exp_f32_e32 v50, v50
	v_mul_f32_e32 v51, 0xbfb8aa3b, v37
	v_exp_f32_e32 v51, v51
	v_pk_mul_f32 v[34:35], v[38:39], v[232:233]
	v_add_f32_e32 v50, 1.0, v50
	v_rcp_f32_e32 v55, v50
	v_mul_f32_e32 v50, 0xbfb8aa3b, v36
	v_exp_f32_e32 v50, v50
	v_add_f32_e32 v51, 1.0, v51
	v_rcp_f32_e32 v51, v51
	v_pk_mul_f32 v[52:53], v[54:55], v[52:53]
	v_add_f32_e32 v50, 1.0, v50
	v_rcp_f32_e32 v50, v50
	v_pk_mul_f32 v[32:33], v[32:33], v[52:53]
	v_pk_mul_f32 v[36:37], v[50:51], v[36:37]
	s_nop 0
	v_pk_mul_f32 v[34:35], v[34:35], v[36:37]
	v_cvt_pk_bf16_f32 v32, v32, v33
	v_cvt_pk_bf16_f32 v33, v34, v35
	global_store_dwordx2 v[48:49], v[32:33], off offset:80
	s_nop 0
	s_waitcnt vmcnt(25)
	v_lshlrev_b32_e32 v38, 16, v152
	v_and_b32_e32 v39, 0xffff0000, v152
	v_mul_f32_e32 v36, 0xbfb8aa3b, v38
	v_exp_f32_e32 v36, v36
	s_waitcnt vmcnt(24)
	v_pk_mul_f32 v[32:33], v[40:41], v[234:235]
	v_add_f32_e32 v36, 1.0, v36
	v_rcp_f32_e32 v50, v36
	v_mul_f32_e32 v36, 0xbfb8aa3b, v39
	v_exp_f32_e32 v36, v36
	s_nop 0
	v_add_f32_e32 v36, 1.0, v36
	v_rcp_f32_e32 v51, v36
	v_lshlrev_b32_e32 v36, 16, v153
	v_and_b32_e32 v37, 0xffff0000, v153
	v_pk_mul_f32 v[38:39], v[50:51], v[38:39]
	s_nop 0
	v_pk_mul_f32 v[32:33], v[32:33], v[38:39]
	v_mul_f32_e32 v38, 0xbfb8aa3b, v36
	v_mul_f32_e32 v39, 0xbfb8aa3b, v37
	v_exp_f32_e32 v38, v38
	v_exp_f32_e32 v39, v39
	v_cvt_pk_bf16_f32 v32, v32, v33
	v_add_f32_e32 v38, 1.0, v38
	v_add_f32_e32 v39, 1.0, v39
	v_rcp_f32_e32 v38, v38
	v_rcp_f32_e32 v39, v39
	s_nop 0
	v_pk_mul_f32 v[36:37], v[38:39], v[36:37]
	v_pk_mul_f32 v[38:39], v[42:43], v[64:65] op_sel_hi:[1,0]
	s_nop 0
	v_pk_mul_f32 v[34:35], v[38:39], v[236:237]
	s_nop 0
	v_pk_mul_f32 v[34:35], v[34:35], v[36:37]
	s_nop 0
	v_cvt_pk_bf16_f32 v33, v34, v35
	global_store_dwordx2 v[48:49], v[32:33], off offset:96
	s_nop 0
	s_waitcnt vmcnt(24)
	v_lshlrev_b32_e32 v38, 16, v154
	v_and_b32_e32 v39, 0xffff0000, v154
	v_mul_f32_e32 v36, 0xbfb8aa3b, v38
	v_exp_f32_e32 v36, v36
	s_nop 0
	v_add_f32_e32 v36, 1.0, v36
	v_rcp_f32_e32 v40, v36
	v_mul_f32_e32 v36, 0xbfb8aa3b, v39
	v_exp_f32_e32 v36, v36
	s_nop 0
	v_add_f32_e32 v36, 1.0, v36
	v_rcp_f32_e32 v41, v36
	v_lshlrev_b32_e32 v36, 16, v155
	v_and_b32_e32 v37, 0xffff0000, v155
	v_pk_mul_f32 v[38:39], v[40:41], v[38:39]
	v_pk_mul_f32 v[40:41], v[44:45], v[64:65] op_sel_hi:[1,0]
	s_waitcnt vmcnt(23)
	v_pk_mul_f32 v[32:33], v[40:41], v[238:239]
	s_nop 0
	v_pk_mul_f32 v[32:33], v[32:33], v[38:39]
	v_mul_f32_e32 v38, 0xbfb8aa3b, v36
	v_mul_f32_e32 v39, 0xbfb8aa3b, v37
	v_exp_f32_e32 v38, v38
	v_exp_f32_e32 v39, v39
	v_cvt_pk_bf16_f32 v32, v32, v33
	v_add_f32_e32 v38, 1.0, v38
	v_add_f32_e32 v39, 1.0, v39
	v_rcp_f32_e32 v38, v38
	v_rcp_f32_e32 v39, v39
	s_nop 0
	v_pk_mul_f32 v[36:37], v[38:39], v[36:37]
	v_pk_mul_f32 v[38:39], v[46:47], v[64:65] op_sel_hi:[1,0]
	s_nop 0
	v_pk_mul_f32 v[34:35], v[38:39], v[240:241]
	s_nop 0
	v_pk_mul_f32 v[34:35], v[34:35], v[36:37]
	s_nop 0
	v_cvt_pk_bf16_f32 v33, v34, v35
	global_store_dwordx2 v[48:49], v[32:33], off offset:112
	s_nop 0
	s_waitcnt vmcnt(23)
	v_lshlrev_b32_e32 v38, 16, v156
	v_and_b32_e32 v39, 0xffff0000, v156
	v_mul_f32_e32 v36, 0xbfb8aa3b, v38
	v_exp_f32_e32 v36, v36
	s_waitcnt vmcnt(22)
	v_pk_mul_f32 v[16:17], v[16:17], v[242:243]
	v_lshlrev_b32_e32 v32, 16, v157
	v_and_b32_e32 v33, 0xffff0000, v157
	v_add_f32_e32 v36, 1.0, v36
	v_rcp_f32_e32 v40, v36
	v_mul_f32_e32 v36, 0xbfb8aa3b, v39
	v_exp_f32_e32 v36, v36
	v_mul_f32_e32 v37, 0xbfb8aa3b, v33
	v_exp_f32_e32 v37, v37
	v_pk_mul_f32 v[18:19], v[18:19], v[244:245]
	v_add_f32_e32 v36, 1.0, v36
	v_rcp_f32_e32 v41, v36
	v_mul_f32_e32 v36, 0xbfb8aa3b, v32
	v_exp_f32_e32 v36, v36
	v_add_f32_e32 v37, 1.0, v37
	v_rcp_f32_e32 v37, v37
	v_pk_mul_f32 v[38:39], v[40:41], v[38:39]
	v_add_f32_e32 v36, 1.0, v36
	v_rcp_f32_e32 v36, v36
	v_pk_mul_f32 v[16:17], v[16:17], v[38:39]
	v_pk_mul_f32 v[32:33], v[36:37], v[32:33]
	s_nop 0
	v_pk_mul_f32 v[18:19], v[18:19], v[32:33]
	v_cvt_pk_bf16_f32 v16, v16, v17
	v_cvt_pk_bf16_f32 v17, v18, v19
	global_store_dwordx2 v[48:49], v[16:17], off offset:128
	s_nop 0
	s_waitcnt vmcnt(22)
	v_lshlrev_b32_e32 v34, 16, v158
	v_and_b32_e32 v35, 0xffff0000, v158
	v_mul_f32_e32 v32, 0xbfb8aa3b, v34
	v_exp_f32_e32 v32, v32
	s_waitcnt vmcnt(21)
	v_pk_mul_f32 v[16:17], v[20:21], v[246:247]
	v_lshlrev_b32_e32 v20, 16, v159
	v_and_b32_e32 v21, 0xffff0000, v159
	v_add_f32_e32 v32, 1.0, v32
	v_rcp_f32_e32 v36, v32
	v_mul_f32_e32 v32, 0xbfb8aa3b, v35
	v_exp_f32_e32 v32, v32
	v_mul_f32_e32 v33, 0xbfb8aa3b, v21
	v_exp_f32_e32 v33, v33
	v_pk_mul_f32 v[18:19], v[22:23], v[248:249]
	v_add_f32_e32 v32, 1.0, v32
	v_rcp_f32_e32 v37, v32
	v_mul_f32_e32 v32, 0xbfb8aa3b, v20
	v_exp_f32_e32 v32, v32
	v_add_f32_e32 v33, 1.0, v33
	v_rcp_f32_e32 v33, v33
	v_pk_mul_f32 v[34:35], v[36:37], v[34:35]
	v_add_f32_e32 v32, 1.0, v32
	v_rcp_f32_e32 v32, v32
	v_pk_mul_f32 v[16:17], v[16:17], v[34:35]
	v_pk_mul_f32 v[20:21], v[32:33], v[20:21]
	s_nop 0
	v_pk_mul_f32 v[18:19], v[18:19], v[20:21]
	v_cvt_pk_bf16_f32 v16, v16, v17
	v_cvt_pk_bf16_f32 v17, v18, v19
	global_store_dwordx2 v[48:49], v[16:17], off offset:144
	s_nop 0
	s_waitcnt vmcnt(21)
	v_lshlrev_b32_e32 v22, 16, v160
	v_and_b32_e32 v23, 0xffff0000, v160
	v_mul_f32_e32 v20, 0xbfb8aa3b, v22
	v_exp_f32_e32 v20, v20
	s_waitcnt vmcnt(20)
	v_pk_mul_f32 v[16:17], v[24:25], v[182:183]
	v_add_f32_e32 v20, 1.0, v20
	v_rcp_f32_e32 v32, v20
	v_mul_f32_e32 v20, 0xbfb8aa3b, v23
	v_exp_f32_e32 v20, v20
	s_nop 0
	v_add_f32_e32 v20, 1.0, v20
	v_rcp_f32_e32 v33, v20
	v_lshlrev_b32_e32 v20, 16, v161
	v_and_b32_e32 v21, 0xffff0000, v161
	v_pk_mul_f32 v[22:23], v[32:33], v[22:23]
	s_nop 0
	v_pk_mul_f32 v[16:17], v[16:17], v[22:23]
	v_mul_f32_e32 v22, 0xbfb8aa3b, v20
	v_mul_f32_e32 v23, 0xbfb8aa3b, v21
	v_exp_f32_e32 v22, v22
	v_exp_f32_e32 v23, v23
	v_cvt_pk_bf16_f32 v16, v16, v17
	v_add_f32_e32 v22, 1.0, v22
	v_add_f32_e32 v23, 1.0, v23
	v_rcp_f32_e32 v22, v22
	v_rcp_f32_e32 v23, v23
	s_nop 0
	v_pk_mul_f32 v[20:21], v[22:23], v[20:21]
	v_pk_mul_f32 v[22:23], v[26:27], v[64:65] op_sel_hi:[1,0]
	s_nop 0
	v_pk_mul_f32 v[18:19], v[22:23], v[184:185]
	s_nop 0
	v_pk_mul_f32 v[18:19], v[18:19], v[20:21]
	s_nop 0
	v_cvt_pk_bf16_f32 v17, v18, v19
	global_store_dwordx2 v[48:49], v[16:17], off offset:160
	s_nop 0
	s_waitcnt vmcnt(20)
	v_lshlrev_b32_e32 v22, 16, v170
	v_and_b32_e32 v23, 0xffff0000, v170
	v_mul_f32_e32 v20, 0xbfb8aa3b, v22
	v_exp_f32_e32 v20, v20
	s_nop 0
	v_add_f32_e32 v20, 1.0, v20
	v_rcp_f32_e32 v24, v20
	v_mul_f32_e32 v20, 0xbfb8aa3b, v23
	v_exp_f32_e32 v20, v20
	s_nop 0
	v_add_f32_e32 v20, 1.0, v20
	v_rcp_f32_e32 v25, v20
	v_lshlrev_b32_e32 v20, 16, v171
	v_and_b32_e32 v21, 0xffff0000, v171
	v_pk_mul_f32 v[22:23], v[24:25], v[22:23]
	v_pk_mul_f32 v[24:25], v[28:29], v[64:65] op_sel_hi:[1,0]
	s_waitcnt vmcnt(19)
	v_pk_mul_f32 v[16:17], v[24:25], v[84:85]
	s_nop 0
	v_pk_mul_f32 v[16:17], v[16:17], v[22:23]
	v_mul_f32_e32 v22, 0xbfb8aa3b, v20
	v_mul_f32_e32 v23, 0xbfb8aa3b, v21
	v_exp_f32_e32 v22, v22
	v_exp_f32_e32 v23, v23
	v_cvt_pk_bf16_f32 v16, v16, v17
	v_add_f32_e32 v22, 1.0, v22
	v_add_f32_e32 v23, 1.0, v23
	v_rcp_f32_e32 v22, v22
	v_rcp_f32_e32 v23, v23
	s_nop 0
	v_pk_mul_f32 v[20:21], v[22:23], v[20:21]
	v_pk_mul_f32 v[22:23], v[30:31], v[64:65] op_sel_hi:[1,0]
	s_nop 0
	v_pk_mul_f32 v[18:19], v[22:23], v[86:87]
	s_nop 0
	v_pk_mul_f32 v[18:19], v[18:19], v[20:21]
	s_nop 0
	v_cvt_pk_bf16_f32 v17, v18, v19
	global_store_dwordx2 v[48:49], v[16:17], off offset:176
	s_nop 0
	s_waitcnt vmcnt(19)
	v_lshlrev_b32_e32 v22, 16, v172
	v_and_b32_e32 v23, 0xffff0000, v172
	v_mul_f32_e32 v20, 0xbfb8aa3b, v22
	v_exp_f32_e32 v20, v20
	s_waitcnt vmcnt(18)
	v_pk_mul_f32 v[0:1], v[0:1], v[92:93]
	v_lshlrev_b32_e32 v16, 16, v173
	v_and_b32_e32 v17, 0xffff0000, v173
	v_add_f32_e32 v20, 1.0, v20
	v_rcp_f32_e32 v24, v20
	v_mul_f32_e32 v20, 0xbfb8aa3b, v23
	v_exp_f32_e32 v20, v20
	v_mul_f32_e32 v21, 0xbfb8aa3b, v17
	v_exp_f32_e32 v21, v21
	v_pk_mul_f32 v[2:3], v[2:3], v[94:95]
	v_add_f32_e32 v20, 1.0, v20
	v_rcp_f32_e32 v25, v20
	v_mul_f32_e32 v20, 0xbfb8aa3b, v16
	v_exp_f32_e32 v20, v20
	v_add_f32_e32 v21, 1.0, v21
	v_rcp_f32_e32 v21, v21
	v_pk_mul_f32 v[22:23], v[24:25], v[22:23]
	v_add_f32_e32 v20, 1.0, v20
	v_rcp_f32_e32 v20, v20
	v_pk_mul_f32 v[0:1], v[0:1], v[22:23]
	v_pk_mul_f32 v[16:17], v[20:21], v[16:17]
	s_nop 0
	v_pk_mul_f32 v[2:3], v[2:3], v[16:17]
	v_cvt_pk_bf16_f32 v0, v0, v1
	v_cvt_pk_bf16_f32 v1, v2, v3
	global_store_dwordx2 v[48:49], v[0:1], off offset:192
	s_nop 0
	s_waitcnt vmcnt(18)
	v_lshlrev_b32_e32 v18, 16, v174
	v_and_b32_e32 v19, 0xffff0000, v174
	v_mul_f32_e32 v16, 0xbfb8aa3b, v18
	v_exp_f32_e32 v16, v16
	s_waitcnt vmcnt(17)
	v_pk_mul_f32 v[0:1], v[4:5], v[102:103]
	v_lshlrev_b32_e32 v4, 16, v175
	v_and_b32_e32 v5, 0xffff0000, v175
	v_add_f32_e32 v16, 1.0, v16
	v_rcp_f32_e32 v20, v16
	v_mul_f32_e32 v16, 0xbfb8aa3b, v19
	v_exp_f32_e32 v16, v16
	v_mul_f32_e32 v17, 0xbfb8aa3b, v5
	v_exp_f32_e32 v17, v17
	v_pk_mul_f32 v[2:3], v[6:7], v[104:105]
	v_add_f32_e32 v16, 1.0, v16
	v_rcp_f32_e32 v21, v16
	v_mul_f32_e32 v16, 0xbfb8aa3b, v4
	v_exp_f32_e32 v16, v16
	v_add_f32_e32 v17, 1.0, v17
	v_rcp_f32_e32 v17, v17
	v_pk_mul_f32 v[18:19], v[20:21], v[18:19]
	v_add_f32_e32 v16, 1.0, v16
	v_rcp_f32_e32 v16, v16
	v_pk_mul_f32 v[0:1], v[0:1], v[18:19]
	v_pk_mul_f32 v[4:5], v[16:17], v[4:5]
	s_nop 0
	v_pk_mul_f32 v[2:3], v[2:3], v[4:5]
	v_cvt_pk_bf16_f32 v0, v0, v1
	v_cvt_pk_bf16_f32 v1, v2, v3
	global_store_dwordx2 v[48:49], v[0:1], off offset:208
	s_nop 0
	s_waitcnt vmcnt(17)
	v_lshlrev_b32_e32 v6, 16, v176
	v_and_b32_e32 v7, 0xffff0000, v176
	v_mul_f32_e32 v4, 0xbfb8aa3b, v6
	v_exp_f32_e32 v4, v4
	s_waitcnt vmcnt(16)
	v_pk_mul_f32 v[0:1], v[8:9], v[122:123]
	v_add_f32_e32 v4, 1.0, v4
	v_rcp_f32_e32 v16, v4
	v_mul_f32_e32 v4, 0xbfb8aa3b, v7
	v_exp_f32_e32 v4, v4
	s_nop 0
	v_add_f32_e32 v4, 1.0, v4
	v_rcp_f32_e32 v17, v4
	v_lshlrev_b32_e32 v4, 16, v177
	v_and_b32_e32 v5, 0xffff0000, v177
	v_pk_mul_f32 v[6:7], v[16:17], v[6:7]
	s_nop 0
	v_pk_mul_f32 v[0:1], v[0:1], v[6:7]
	v_mul_f32_e32 v6, 0xbfb8aa3b, v4
	v_mul_f32_e32 v7, 0xbfb8aa3b, v5
	v_exp_f32_e32 v6, v6
	v_exp_f32_e32 v7, v7
	v_cvt_pk_bf16_f32 v0, v0, v1
	v_add_f32_e32 v6, 1.0, v6
	v_add_f32_e32 v7, 1.0, v7
	v_rcp_f32_e32 v6, v6
	v_rcp_f32_e32 v7, v7
	s_nop 0
	v_pk_mul_f32 v[4:5], v[6:7], v[4:5]
	v_pk_mul_f32 v[6:7], v[10:11], v[64:65] op_sel_hi:[1,0]
	s_nop 0
	v_pk_mul_f32 v[2:3], v[6:7], v[124:125]
	s_nop 0
	v_pk_mul_f32 v[2:3], v[2:3], v[4:5]
	s_nop 0
	v_cvt_pk_bf16_f32 v1, v2, v3
	global_store_dwordx2 v[48:49], v[0:1], off offset:224
	s_nop 0
	s_waitcnt vmcnt(16)
	v_lshlrev_b32_e32 v6, 16, v178
	v_and_b32_e32 v7, 0xffff0000, v178
	v_mul_f32_e32 v0, 0xbfb8aa3b, v6
	v_exp_f32_e32 v0, v0
	s_nop 0
	v_add_f32_e32 v0, 1.0, v0
	v_rcp_f32_e32 v8, v0
	v_mul_f32_e32 v0, 0xbfb8aa3b, v7
	v_exp_f32_e32 v0, v0
	s_nop 0
	v_add_f32_e32 v0, 1.0, v0
	v_rcp_f32_e32 v9, v0
	v_lshlrev_b32_e32 v0, 16, v179
	v_and_b32_e32 v1, 0xffff0000, v179
	v_pk_mul_f32 v[6:7], v[8:9], v[6:7]
	v_pk_mul_f32 v[8:9], v[12:13], v[64:65] op_sel_hi:[1,0]
	s_waitcnt vmcnt(15)
	v_pk_mul_f32 v[2:3], v[8:9], v[130:131]
	s_nop 0
	v_pk_mul_f32 v[2:3], v[2:3], v[6:7]
	v_mul_f32_e32 v6, 0xbfb8aa3b, v0
	v_mul_f32_e32 v7, 0xbfb8aa3b, v1
	v_exp_f32_e32 v6, v6
	v_exp_f32_e32 v7, v7
	v_cvt_pk_bf16_f32 v2, v2, v3
	v_add_f32_e32 v6, 1.0, v6
	v_add_f32_e32 v7, 1.0, v7
	v_rcp_f32_e32 v6, v6
	v_rcp_f32_e32 v7, v7
	s_nop 0
	v_pk_mul_f32 v[0:1], v[6:7], v[0:1]
	v_pk_mul_f32 v[6:7], v[14:15], v[64:65] op_sel_hi:[1,0]
	s_nop 0
	v_pk_mul_f32 v[4:5], v[6:7], v[132:133]
	s_nop 0
	v_pk_mul_f32 v[0:1], v[4:5], v[0:1]
	s_nop 0
	v_cvt_pk_bf16_f32 v3, v0, v1
	global_store_dwordx2 v[48:49], v[2:3], off offset:240
	s_barrier
